# grid barrier between P2 and P4 replaced by dependency counters (cumsum+kmax done -> fox units, all workgroups out of P2 -> scan units); kmax slices right behind cumsum; P4 order fox-long first
# speedup vs baseline: 1.0083x; 1.0083x over previous
; DI void unpack8(uint4 v, float* f) { f[0] = bflo(v.x); f[1] = bfhi(v.x); f[2] = bflo(v.y); f[3] = bfhi(v.y); f[4] = bflo(v.z); f[5] = bfhi(v.z); f[6] = bflo(v.w); f[7] = bfhi(v.w); }
; DI float ex2(float x) { return __builtin_amdgcn_exp2f(x); }
; DI void norm_unit(const Params& p, int layer, int half, int nu, int tid) { norm_rows(p, layer, half * HROWS + nu * 64, 64, 0, 8, tid); }
; #define otid() otid_(wbase)
; DI void ret_local_unit(const Params& p, int hf, int bl, int c, int hd, unsigned char* shm, int tid) {
;     ...
;   const float lg = logf(1.0f - ex2(-5.0f - (float)hd));
; #pragma unroll
;   for (int it = 0; it < 2; ++it) {
;     const int idx = tid + it * NTHR, j = idx >> 3, dg = idx & 7;
;     const bf16_t* base = projb + (size_t)(c * 128 + j) * NP;
;     float k1[8], k2[8]; unpack8(*(const uint4*)(base + C_RK + hd * 128 + dg * 8), k1); unpack8(*(const uint4*)(base + C_RK + hd * 128 + 64 + dg * 8), k2);
;     const float w = __expf(lg * (float)(127 - j)) * 0.08838834764831845f;
; __global__ void __launch_bounds__(NTHR) mega(Params p) {
;     ...
;           int u = u0;
;           if (u >= 784 + n_fill) break;
;           if (u >= 16 && u < 16 + n_fill) { norm_unit(p, layer, 1, u - 16, otid()); continue; }
;           if (u >= 16) u -= n_fill;
;           if (u < 16) fox_cumsum_unit(p, hf, u >> 3, u & 7, shm, otid());
;           else if (u < 272) { const int k = u - 16; ssd_local_unit(p, layer, hf, k >> 7, (k >> 1) & 63, k & 1, shm, otid()); }
;           else { const int k = u - 272; ret_local_unit(p, hf, k >> 8, (k >> 2) & 63, k & 3, shm, otid()); }
.LBB0_241:
	s_or_b64 exec, exec, s[0:1]
	s_waitcnt lgkmcnt(0)
	s_barrier
	ds_read_b32 v0, v161 offset:16
	s_mov_b64 s[0:1], -1
	s_waitcnt lgkmcnt(0)
	v_cmp_le_i32_e32 vcc, s56, v0
	v_readfirstlane_b32 s58, v0
	s_cbranch_vccnz .LBB0_236
	s_cmp_gt_i32 s58, 15
	s_cselect_b64 s[0:1], -1, 0
	s_cmp_lt_i32 s58, s57
	s_cselect_b64 s[4:5], -1, 0
	s_and_b64 s[4:5], s[0:1], s[4:5]
	s_andn2_b64 vcc, exec, s[4:5]
	s_mov_b64 s[4:5], -1
	s_cbranch_vccz .LBB0_353
	s_and_b64 s[0:1], s[0:1], exec
	s_cselect_b32 s0, s13, 0
	s_sub_i32 s24, s58, s0
	s_add_i32 s0, s24, 0x300
	s_add_i32 s1, s24, 0xffffffc0
	s_cmp_lt_u32 s24, 0x50
	s_cselect_b32 s0, s0, s1
	s_cmp_lt_u32 s24, 16
	s_cselect_b32 s24, s24, s0
	s_cmp_gt_i32 s24, 15
	s_mov_b64 s[0:1], -1
	s_cbranch_scc0 .LBB0_312
	s_cmpk_gt_u32 s24, 0x10f
	s_cbranch_scc0 .LBB0_246
	s_cmpk_gt_u32 s24, 0x30f
	s_cbranch_scc1 .Lkmx_unit
	s_add_i32 s8, s24, 0xfffffef0
	s_lshr_b32 s4, s8, 8
	s_mul_i32 s2, s4, 0x3400000
	s_bfe_u32 s10, s8, 0x60002
	s_and_b32 s9, s58, 3
	s_lshl_b64 s[0:1], s[2:3], 1
	s_add_u32 s6, s38, s0
	s_addc_u32 s7, s39, s1
	s_lshl_b32 s0, s4, 13
	v_cvt_f32_ubyte0_e32 v0, s9
	s_add_i32 s0, s0, s68
	s_lshl_b32 s11, s10, 7
	v_sub_f32_e32 v0, 0xc0a00000, v0
	s_or_b32 s0, s0, s11
	v_exp_f32_e32 v0, v0
	s_lshl_b32 s2, s0, 6
	s_lshl_b64 s[0:1], s[2:3], 3
	v_readlane_b32 s2, v252, 45
	s_add_u32 s4, s2, s0
	v_readlane_b32 s0, v252, 46
	s_addc_u32 s5, s0, s1
	v_sub_f32_e32 v0, 1.0, v0
	s_mov_b32 s0, 0x800000
	v_cmp_gt_f32_e32 vcc, s0, v0
	s_and_b64 s[0:1], vcc, exec
	s_cselect_b32 s0, 32, 0
	v_ldexp_f32 v0, v0, s0
	v_log_f32_e32 v0, v0
	s_mov_b32 s0, 0x3f317217
	v_mov_b32_e32 v18, v163
	v_mul_f32_e32 v1, 0x3f317217, v0
	v_fma_f32 v1, v0, s0, -v1
	v_fmac_f32_e32 v1, 0x3377d1cf, v0
	s_mov_b32 s0, 0x7f800000
	v_fmac_f32_e32 v1, 0x3f317217, v0
	v_cmp_lt_f32_e64 s[0:1], |v0|, s0
	v_ashrrev_i32_e32 v13, 3, v18
	v_mov_b64_e32 v[14:15], s[6:7]
	v_cndmask_b32_e64 v0, v0, v1, s[0:1]
	v_cndmask_b32_e32 v1, 0, v201, vcc
	v_sub_f32_e32 v21, v0, v1
	v_and_b32_e32 v0, 7, v18
	v_lshlrev_b32_e32 v20, 3, v0
	v_lshlrev_b32_e32 v160, 4, v0
	v_lshlrev_b32_e32 v12, 5, v0
	v_add_u32_e32 v0, s11, v13
	v_mad_i64_i32 v[0:1], s[0:1], v0, s65, v[14:15]
	s_lshl_b32 s2, s9, 8
	v_lshl_add_u64 v[16:17], v[0:1], 0, s[2:3]
	v_lshl_add_u64 v[4:5], v[16:17], 0, v[160:161]
	v_lshl_add_u64 v[208:209], v[16:17], 0, v[160:161]
	global_load_dwordx4 v[100:103], v[208:209], off offset:1024
	global_load_dwordx4 v[104:107], v[208:209], off offset:1152
	v_lshl_or_b32 v210, v13, 6, v20
	v_mov_b32_e32 v211, v161
	v_lshl_add_u64 v[210:211], v[210:211], 3, s[4:5]
	global_load_dwordx4 v[108:111], v[210:211], off offset:48
	global_load_dwordx4 v[112:115], v[210:211], off offset:32
	global_load_dwordx4 v[116:119], v[210:211], off offset:16
	global_load_dwordx4 v[120:123], v[210:211], off
	v_mov_b32_e32 v212, v12
	v_mov_b32_e32 v213, v161
	v_lshl_add_u64 v[212:213], v[16:17], 0, v[212:213]
	global_load_dwordx4 v[124:127], v[212:213], off offset:2048
	global_load_dwordx4 v[128:131], v[212:213], off offset:2064
	v_add_u32_e32 v222, 64, v13
	v_add_u32_e32 v223, s11, v222
	v_mad_i64_i32 v[214:215], s[0:1], v223, s65, v[14:15]
	v_lshl_add_u64 v[214:215], v[214:215], 0, s[2:3]
	v_lshl_add_u64 v[216:217], v[214:215], 0, v[160:161]
	global_load_dwordx4 v[132:135], v[216:217], off offset:1024
	global_load_dwordx4 v[136:139], v[216:217], off offset:1152
	v_lshl_or_b32 v218, v222, 6, v20
	v_mov_b32_e32 v219, v161
	v_lshl_add_u64 v[218:219], v[218:219], 3, s[4:5]
	global_load_dwordx4 v[140:143], v[218:219], off offset:48
	global_load_dwordx4 v[144:147], v[218:219], off offset:32
	global_load_dwordx4 v[148:151], v[218:219], off offset:16
	global_load_dwordx4 v[152:155], v[218:219], off
	v_mov_b32_e32 v220, v12
	v_mov_b32_e32 v221, v161
	v_lshl_add_u64 v[220:221], v[214:215], 0, v[220:221]
	global_load_dwordx4 v[156:159], v[220:221], off offset:2048
	global_load_dwordx4 v[204:207], v[220:221], off offset:2064
	v_add_u32_e32 v19, 32, v12
	s_waitcnt vmcnt(15)
	v_mov_b32_e32 v0, v100
	v_mov_b32_e32 v1, v101
	v_mov_b32_e32 v2, v102
	v_mov_b32_e32 v3, v103
	v_lshlrev_b32_e32 v26, 16, v0
	v_and_b32_e32 v27, 0xffff0000, v0
	v_lshlrev_b32_e32 v28, 16, v1
	v_and_b32_e32 v29, 0xffff0000, v1
	v_lshlrev_b32_e32 v30, 16, v2
	v_and_b32_e32 v31, 0xffff0000, v2
	v_lshlrev_b32_e32 v32, 16, v3
	v_and_b32_e32 v33, 0xffff0000, v3
	s_waitcnt vmcnt(14)
	v_mov_b32_e32 v0, v104
	v_mov_b32_e32 v1, v105
	v_mov_b32_e32 v2, v106
	v_mov_b32_e32 v3, v107
	v_lshlrev_b32_e32 v34, 16, v0
	v_and_b32_e32 v35, 0xffff0000, v0
	v_sub_u32_e32 v0, 0x7f, v13
	v_cvt_f32_i32_e32 v0, v0
	v_lshlrev_b32_e32 v36, 16, v1
	v_and_b32_e32 v37, 0xffff0000, v1
	v_lshlrev_b32_e32 v38, 16, v2
	v_mul_f32_e32 v0, v21, v0
	v_mul_f32_e32 v0, 0x3fb8aa3b, v0
	v_exp_f32_e32 v0, v0
	v_and_b32_e32 v39, 0xffff0000, v2
	v_lshlrev_b32_e32 v40, 16, v3
	v_and_b32_e32 v41, 0xffff0000, v3
	v_mul_f32_e32 v42, 0x3db504f3, v0
	v_lshl_or_b32 v0, v13, 6, v20
	v_ashrrev_i32_e32 v1, 31, v0
	v_lshl_add_u64 v[22:23], v[0:1], 3, s[4:5]
	s_nop 0
	s_waitcnt vmcnt(10)
; DI void unpack8(uint4 v, float* f) { f[0] = bflo(v.x); f[1] = bfhi(v.x); f[2] = bflo(v.y); f[3] = bfhi(v.y); f[4] = bflo(v.z); f[5] = bfhi(v.z); f[6] = bflo(v.w); f[7] = bfhi(v.w); }
; DI uint4 pack8(const float* f) { uint4 r; r.x = pk2(f[0], f[1]); r.y = pk2(f[2], f[3]); r.z = pk2(f[4], f[5]); r.w = pk2(f[6], f[7]); return r; }
; DI void ret_local_unit(const Params& p, int hf, int bl, int c, int hd, unsigned char* shm, int tid) {
;     ...
;     float k1[8], k2[8]; unpack8(*(const uint4*)(base + C_RK + hd * 128 + dg * 8), k1); unpack8(*(const uint4*)(base + C_RK + hd * 128 + 64 + dg * 8), k2);
;     const float w = __expf(lg * (float)(127 - j)) * 0.08838834764831845f;
;     float o1[8], o2[8];
; #pragma unroll
;     for (int e = 0; e < 8; ++e) {
;       const float2 t = cs[j * 64 + dg * 8 + e];
;       o1[e] = (k1[e] * t.x - k2[e] * t.y) * w; o2[e] = (k1[e] * t.y + k2[e] * t.x) * w;
;     }
;     *(uint4*)(sK + j * LD + dg * 8) = pack8(o1); *(uint4*)(sK + j * LD + 64 + dg * 8) = pack8(o2);
;     *(uint4*)(sV + j * LD + dg * 16) = *(const uint4*)(base + C_RV + hd * 128 + dg * 16);
;     *(uint4*)(sV + j * LD + dg * 16 + 8) = *(const uint4*)(base + C_RV + hd * 128 + dg * 16 + 8);
;   }
;   __syncthreads();
	v_mov_b32_e32 v0, v108
	v_mov_b32_e32 v1, v109
	v_mov_b32_e32 v2, v110
	v_mov_b32_e32 v3, v111
	v_mov_b32_e32 v4, v112
	v_mov_b32_e32 v5, v113
	v_mov_b32_e32 v6, v114
	v_mov_b32_e32 v7, v115
	v_mov_b32_e32 v8, v116
	v_mov_b32_e32 v9, v117
	v_mov_b32_e32 v10, v118
	v_mov_b32_e32 v11, v119
	v_mov_b32_e32 v22, v120
	v_mov_b32_e32 v23, v121
	v_mov_b32_e32 v24, v122
	v_mov_b32_e32 v25, v123
	v_mul_f32_e32 v43, v23, v34
	v_mul_f32_e32 v23, v23, v26
	v_fmac_f32_e32 v23, v22, v34
	v_fma_f32 v43, v22, v26, -v43
	v_mul_f32_e32 v22, v42, v23
	v_mul_f32_e32 v23, v25, v35
	v_mul_f32_e32 v25, v25, v27
	v_fmac_f32_e32 v25, v24, v35
	v_fma_f32 v23, v24, v27, -v23
	v_mul_f32_e32 v24, v42, v25
	v_mul_f32_e32 v25, v9, v36
	v_mul_f32_e32 v9, v9, v28
	v_fmac_f32_e32 v9, v8, v36
	v_fma_f32 v25, v8, v28, -v25
	v_mul_f32_e32 v8, v42, v9
	v_mul_f32_e32 v9, v11, v37
	v_mul_f32_e32 v11, v11, v29
	v_fmac_f32_e32 v11, v10, v37
	v_fma_f32 v9, v10, v29, -v9
	v_mul_f32_e32 v10, v42, v11
	v_mul_f32_e32 v11, v5, v38
	v_mul_f32_e32 v5, v5, v30
	v_fmac_f32_e32 v5, v4, v38
	v_fma_f32 v11, v4, v30, -v11
	v_mul_f32_e32 v4, v42, v5
	v_mul_f32_e32 v5, v7, v39
	v_mul_f32_e32 v7, v7, v31
	v_fmac_f32_e32 v7, v6, v39
	v_fma_f32 v5, v6, v31, -v5
	v_mul_f32_e32 v6, v42, v7
	v_mul_f32_e32 v7, v1, v40
	v_mul_f32_e32 v1, v1, v32
	v_fma_f32 v7, v0, v32, -v7
	v_fmac_f32_e32 v1, v0, v40
	v_mul_f32_e32 v0, v3, v41
	v_fma_f32 v0, v2, v33, -v0
	v_mul_f32_e32 v27, v42, v0
	v_mul_f32_e32 v0, v3, v33
	v_mul_f32_e32 v7, v42, v7
	v_fmac_f32_e32 v0, v2, v41
	v_mul_f32_e32 v43, v42, v43
	v_mul_f32_e32 v23, v42, v23
	v_mul_f32_e32 v25, v42, v25
	v_mul_f32_e32 v9, v42, v9
	v_mul_f32_e32 v11, v42, v11
	v_mul_f32_e32 v5, v42, v5
	v_mul_f32_e32 v26, v42, v1
	v_mul_f32_e32 v28, v42, v0
	v_cvt_pk_bf16_f32 v0, v43, v23
	v_cvt_pk_bf16_f32 v1, v25, v9
	v_cvt_pk_bf16_f32 v2, v11, v5
	v_cvt_pk_bf16_f32 v3, v7, v27
	v_mul_lo_u32 v7, v13, s66
	v_add3_u32 v5, 32, v7, v160
	v_mov_b32_e32 v13, v161
	ds_write_b128 v5, v[0:3]
	v_cvt_pk_bf16_f32 v0, v22, v24
	v_cvt_pk_bf16_f32 v1, v8, v10
	v_cvt_pk_bf16_f32 v2, v4, v6
	v_cvt_pk_bf16_f32 v3, v26, v28
	ds_write_b128 v5, v[0:3] offset:128
	v_lshl_add_u64 v[4:5], v[16:17], 0, v[12:13]
	v_add_u32_e32 v6, v19, v7
	s_waitcnt vmcnt(9)
	v_mov_b32_e32 v0, v124
	v_mov_b32_e32 v1, v125
	v_mov_b32_e32 v2, v126
	v_mov_b32_e32 v3, v127
	ds_write_b128 v6, v[0:3] offset:34816
	s_waitcnt vmcnt(8)
	v_mov_b32_e32 v0, v128
	v_mov_b32_e32 v1, v129
	v_mov_b32_e32 v2, v130
	v_mov_b32_e32 v3, v131
	ds_write_b128 v6, v[0:3] offset:34832
	v_add_u32_e32 v0, 0x200, v18
	v_ashrrev_i32_e32 v24, 3, v0
	v_add_u32_e32 v0, s11, v24
	v_mad_i64_i32 v[0:1], s[0:1], v0, s65, v[14:15]
	v_lshl_add_u64 v[0:1], v[0:1], 0, s[2:3]
	v_lshl_add_u64 v[6:7], v[0:1], 0, v[160:161]
	s_and_b32 s0, s8, 0x3ff00
	s_lshl_b32 s1, s10, 2
	s_or_b32 s0, s1, s0
	s_or_b32 s0, s0, s9
	s_lshl_b32 s2, s0, 14
	s_lshl_b64 s[0:1], s[2:3], 1
	v_readlane_b32 s2, v253, 28
	s_add_u32 s0, s2, s0
	v_readlane_b32 s2, v253, 29
	s_addc_u32 s1, s2, s1
	s_waitcnt vmcnt(7)
	v_mov_b32_e32 v2, v132
	v_mov_b32_e32 v3, v133
	v_mov_b32_e32 v4, v134
	v_mov_b32_e32 v5, v135
	v_lshlrev_b32_e32 v25, 16, v2
	v_and_b32_e32 v26, 0xffff0000, v2
	v_lshlrev_b32_e32 v27, 16, v3
	v_and_b32_e32 v28, 0xffff0000, v3
	v_lshlrev_b32_e32 v29, 16, v4
	v_and_b32_e32 v30, 0xffff0000, v4
	v_lshlrev_b32_e32 v31, 16, v5
	v_and_b32_e32 v32, 0xffff0000, v5
	s_waitcnt vmcnt(6)
	v_mov_b32_e32 v2, v136
	v_mov_b32_e32 v3, v137
	v_mov_b32_e32 v4, v138
	v_mov_b32_e32 v5, v139
	v_lshlrev_b32_e32 v33, 16, v2
	v_and_b32_e32 v34, 0xffff0000, v2
	v_sub_u32_e32 v2, 0x7f, v24
	v_cvt_f32_i32_e32 v2, v2
	v_lshlrev_b32_e32 v35, 16, v3
	v_and_b32_e32 v36, 0xffff0000, v3
	v_lshlrev_b32_e32 v37, 16, v4
	v_mul_f32_e32 v2, v21, v2
	v_mul_f32_e32 v2, 0x3fb8aa3b, v2
	v_exp_f32_e32 v2, v2
	v_and_b32_e32 v38, 0xffff0000, v4
	v_lshlrev_b32_e32 v39, 16, v5
	v_and_b32_e32 v40, 0xffff0000, v5
	v_mul_f32_e32 v41, 0x3db504f3, v2
	v_lshl_or_b32 v2, v24, 6, v20
	v_ashrrev_i32_e32 v3, 31, v2
	v_lshl_add_u64 v[10:11], v[2:3], 3, s[4:5]
	s_waitcnt vmcnt(2)
	v_mov_b32_e32 v2, v140
	v_mov_b32_e32 v3, v141
	v_mov_b32_e32 v4, v142
	v_mov_b32_e32 v5, v143
	v_mov_b32_e32 v6, v144
	v_mov_b32_e32 v7, v145
	v_mov_b32_e32 v8, v146
	v_mov_b32_e32 v9, v147
	v_mov_b32_e32 v14, v148
	v_mov_b32_e32 v15, v149
	v_mov_b32_e32 v16, v150
	v_mov_b32_e32 v17, v151
	v_mov_b32_e32 v20, v152
	v_mov_b32_e32 v21, v153
	v_mov_b32_e32 v22, v154
	v_mov_b32_e32 v23, v155
	v_mul_f32_e32 v10, v21, v33
	v_mul_f32_e32 v11, v21, v25
	v_fma_f32 v10, v20, v25, -v10
	v_fmac_f32_e32 v11, v20, v33
	v_mul_f32_e32 v20, v23, v34
	v_mul_f32_e32 v21, v23, v26
	v_fma_f32 v20, v22, v26, -v20
	v_fmac_f32_e32 v21, v22, v34
	v_mul_f32_e32 v22, v15, v35
	v_mul_f32_e32 v15, v15, v27
	v_fmac_f32_e32 v15, v14, v35
	v_fma_f32 v22, v14, v27, -v22
	v_mul_f32_e32 v14, v41, v15
	v_mul_f32_e32 v15, v17, v36
	v_mul_f32_e32 v17, v17, v28
	v_fmac_f32_e32 v17, v16, v36
	v_fma_f32 v15, v16, v28, -v15
	v_mul_f32_e32 v16, v41, v17
	v_mul_f32_e32 v17, v7, v37
	v_mul_f32_e32 v7, v7, v29
	v_fmac_f32_e32 v7, v6, v37
	v_fma_f32 v17, v6, v29, -v17
	v_mul_f32_e32 v6, v41, v7
	v_mul_f32_e32 v7, v9, v38
	v_mul_f32_e32 v9, v9, v30
	v_fmac_f32_e32 v9, v8, v38
	v_fma_f32 v7, v8, v30, -v7
	v_mul_f32_e32 v8, v41, v9
	v_mul_f32_e32 v9, v3, v39
	v_mul_f32_e32 v3, v3, v31
	v_fma_f32 v9, v2, v31, -v9
	v_fmac_f32_e32 v3, v2, v39
	v_mul_f32_e32 v2, v5, v40
	v_fma_f32 v2, v4, v32, -v2
	v_mul_f32_e32 v25, v41, v2
	v_mul_f32_e32 v2, v5, v32
	v_mul_f32_e32 v7, v41, v7
	v_fmac_f32_e32 v2, v4, v40
	v_mul_f32_e32 v10, v41, v10
	v_mul_f32_e32 v20, v41, v20
	v_mul_f32_e32 v22, v41, v22
	v_mul_f32_e32 v15, v41, v15
	v_mul_f32_e32 v17, v41, v17
	v_mul_f32_e32 v9, v41, v9
	v_mul_f32_e32 v23, v41, v3
	v_mul_f32_e32 v26, v41, v2
	v_cvt_pk_bf16_f32 v2, v10, v20
	v_cvt_pk_bf16_f32 v3, v22, v15
	v_cvt_pk_bf16_f32 v4, v17, v7
	v_mul_lo_u32 v7, v24, s66
	v_cvt_pk_bf16_f32 v5, v9, v25
	v_add3_u32 v9, 32, v7, v160
	v_mul_f32_e32 v11, v41, v11
	v_mul_f32_e32 v21, v41, v21
	ds_write_b128 v9, v[2:5]
	v_cvt_pk_bf16_f32 v2, v11, v21
	v_cvt_pk_bf16_f32 v3, v14, v16
	v_cvt_pk_bf16_f32 v4, v6, v8
	v_cvt_pk_bf16_f32 v5, v23, v26
	ds_write_b128 v9, v[2:5] offset:128
	v_lshl_add_u64 v[4:5], v[0:1], 0, v[12:13]
	v_add_u32_e32 v6, v19, v7
	s_waitcnt vmcnt(1)
	v_mov_b32_e32 v0, v156
	v_mov_b32_e32 v1, v157
	v_mov_b32_e32 v2, v158
	v_mov_b32_e32 v3, v159
	ds_write_b128 v6, v[0:3] offset:34816
	v_ashrrev_i32_e32 v4, 6, v18
	v_and_b32_e32 v5, 15, v18
	v_lshlrev_b32_e32 v5, 7, v5
	s_waitcnt vmcnt(0)
	v_mov_b32_e32 v0, v204
	v_mov_b32_e32 v1, v205
	v_mov_b32_e32 v2, v206
	v_mov_b32_e32 v3, v207
	ds_write_b128 v6, v[0:3] offset:34832
	v_lshrrev_b32_e32 v0, 1, v18
	v_and_b32_e32 v160, 24, v0
	v_bfe_u32 v0, v18, 2, 2
	v_or_b32_e32 v0, v160, v0
	v_lshlrev_b32_e32 v1, 3, v18
	v_mul_u32_u24_e32 v0, 0x88, v0
	v_and_b32_e32 v1, 24, v1
	v_lshlrev_b32_e32 v0, 1, v0
	v_add3_u32 v6, 32, v1, v0
	v_lshl_add_u32 v7, v4, 5, v6
	s_waitcnt lgkmcnt(0)
	s_barrier
; DI f32x4 mmaT(bf16x8 a_m, bf16x8 b_n, f32x4 c) { return __builtin_amdgcn_mfma_f32_16x16x32_bf16(b_n, a_m, c, 0, 0, 0); }
; DI void ret_local_unit(const Params& p, int hf, int bl, int c, int hd, unsigned char* shm, int tid) {
;     ...
;   const int wid = tid >> 6, lane = tid & 63, fr = lane & 15, fq = lane >> 4;
;   f32x4 acc[8];
; #pragma unroll
;   for (int n = 0; n < 8; ++n) acc[n] = (f32x4){0.f, 0.f, 0.f, 0.f};
; #pragma unroll
;   for (int ks = 0; ks < 4; ++ks) {
;     const bf16x8 a = frag_tr(sV, LD, 32 * ks, 16 * wid, fr, fq);
; #pragma unroll
;     for (int n = 0; n < 8; ++n) acc[n] = mmaT(a, frag_tr(sK, LD, 32 * ks, 16 * n, fr, fq), acc[n]);
;   }
	ds_read_b64_tr_b16 v[0:1], v7 offset:34816
	ds_read_b64_tr_b16 v[2:3], v7 offset:35904
	ds_read_b64_tr_b16 v[10:11], v6 offset:1088
	ds_read_b64_tr_b16 v[8:9], v6
	ds_read_b64_tr_b16 v[12:13], v6 offset:32
	ds_read_b64_tr_b16 v[14:15], v6 offset:1120
	ds_read_b64_tr_b16 v[16:17], v6 offset:64
	ds_read_b64_tr_b16 v[18:19], v6 offset:1152
	ds_read_b64_tr_b16 v[20:21], v6 offset:96
	ds_read_b64_tr_b16 v[22:23], v6 offset:1184
	ds_read_b64_tr_b16 v[24:25], v6 offset:128
	ds_read_b64_tr_b16 v[26:27], v6 offset:1216
	ds_read_b64_tr_b16 v[28:29], v6 offset:160
	ds_read_b64_tr_b16 v[30:31], v6 offset:1248
	ds_read_b64_tr_b16 v[32:33], v6 offset:192
	ds_read_b64_tr_b16 v[34:35], v6 offset:1280
	ds_read_b64_tr_b16 v[36:37], v6 offset:224
	ds_read_b64_tr_b16 v[38:39], v6 offset:1312
	s_waitcnt lgkmcnt(14)
	v_mfma_f32_16x16x32_bf16 v[8:11], v[8:11], v[0:3], 0
	v_lshl_or_b32 v4, v4, 11, v5
	v_ashrrev_i32_e32 v5, 31, v4
	v_lshl_add_u64 v[4:5], v[4:5], 1, s[0:1]
	s_waitcnt lgkmcnt(12)
	v_mfma_f32_16x16x32_bf16 v[12:15], v[12:15], v[0:3], 0
	v_lshl_add_u64 v[4:5], v[4:5], 0, v[160:161]
	s_mov_b64 s[0:1], 0
	s_waitcnt lgkmcnt(10)
	v_mfma_f32_16x16x32_bf16 v[16:19], v[16:19], v[0:3], 0
	s_waitcnt lgkmcnt(8)
	v_mfma_f32_16x16x32_bf16 v[20:23], v[20:23], v[0:3], 0
	s_waitcnt lgkmcnt(6)
	v_mfma_f32_16x16x32_bf16 v[24:27], v[24:27], v[0:3], 0
	s_waitcnt lgkmcnt(4)
	v_mfma_f32_16x16x32_bf16 v[28:31], v[28:31], v[0:3], 0
	s_waitcnt lgkmcnt(2)
	v_mfma_f32_16x16x32_bf16 v[32:35], v[32:35], v[0:3], 0
	s_waitcnt lgkmcnt(0)
	v_mfma_f32_16x16x32_bf16 v[0:3], v[36:39], v[0:3], 0
	ds_read_b64_tr_b16 v[36:37], v7 offset:43520
	ds_read_b64_tr_b16 v[38:39], v7 offset:44608
	ds_read_b64_tr_b16 v[40:41], v6 offset:8704
	ds_read_b64_tr_b16 v[42:43], v6 offset:9792
	s_waitcnt lgkmcnt(0)
	v_mfma_f32_16x16x32_bf16 v[8:11], v[40:43], v[36:39], v[8:11]
	ds_read_b64_tr_b16 v[40:41], v6 offset:8736
	ds_read_b64_tr_b16 v[42:43], v6 offset:9824
	s_waitcnt lgkmcnt(0)
	v_mfma_f32_16x16x32_bf16 v[12:15], v[40:43], v[36:39], v[12:15]
	ds_read_b64_tr_b16 v[40:41], v6 offset:8768
	ds_read_b64_tr_b16 v[42:43], v6 offset:9856
	s_waitcnt lgkmcnt(0)
	v_mfma_f32_16x16x32_bf16 v[16:19], v[40:43], v[36:39], v[16:19]
	ds_read_b64_tr_b16 v[40:41], v6 offset:8800
	ds_read_b64_tr_b16 v[42:43], v6 offset:9888
	s_waitcnt lgkmcnt(0)
	v_mfma_f32_16x16x32_bf16 v[20:23], v[40:43], v[36:39], v[20:23]
	ds_read_b64_tr_b16 v[40:41], v6 offset:8832
	ds_read_b64_tr_b16 v[42:43], v6 offset:9920
	s_waitcnt lgkmcnt(0)
	v_mfma_f32_16x16x32_bf16 v[24:27], v[40:43], v[36:39], v[24:27]
	ds_read_b64_tr_b16 v[40:41], v6 offset:8864
	ds_read_b64_tr_b16 v[42:43], v6 offset:9952
	s_waitcnt lgkmcnt(0)
	v_mfma_f32_16x16x32_bf16 v[28:31], v[40:43], v[36:39], v[28:31]
	ds_read_b64_tr_b16 v[40:41], v6 offset:8896
	ds_read_b64_tr_b16 v[42:43], v6 offset:9984
	s_waitcnt lgkmcnt(0)
	v_mfma_f32_16x16x32_bf16 v[32:35], v[40:43], v[36:39], v[32:35]
	ds_read_b64_tr_b16 v[40:41], v6 offset:8928
	ds_read_b64_tr_b16 v[42:43], v6 offset:10016
	s_waitcnt lgkmcnt(0)
	v_mfma_f32_16x16x32_bf16 v[0:3], v[40:43], v[36:39], v[0:3]
	ds_read_b64_tr_b16 v[36:37], v7 offset:52224
	ds_read_b64_tr_b16 v[38:39], v7 offset:53312
	ds_read_b64_tr_b16 v[40:41], v6 offset:17408
	ds_read_b64_tr_b16 v[42:43], v6 offset:18496
	s_waitcnt lgkmcnt(0)
	v_mfma_f32_16x16x32_bf16 v[8:11], v[40:43], v[36:39], v[8:11]
	ds_read_b64_tr_b16 v[40:41], v6 offset:17440
	ds_read_b64_tr_b16 v[42:43], v6 offset:18528
	s_waitcnt lgkmcnt(0)
; DI unsigned pk2(float lo, float hi) { unsigned r; asm volatile("v_cvt_pk_bf16_f32 %0, %1, %2" : "=v"(r) : "v"(lo), "v"(hi)); return r; }
; DI f32x4 mmaT(bf16x8 a_m, bf16x8 b_n, f32x4 c) { return __builtin_amdgcn_mfma_f32_16x16x32_bf16(b_n, a_m, c, 0, 0, 0); }
; DI void ret_local_unit(const Params& p, int hf, int bl, int c, int hd, unsigned char* shm, int tid) {
;     ...
; #pragma unroll
;   for (int ks = 0; ks < 4; ++ks) {
;     const bf16x8 a = frag_tr(sV, LD, 32 * ks, 16 * wid, fr, fq);
; #pragma unroll
;     for (int n = 0; n < 8; ++n) acc[n] = mmaT(a, frag_tr(sK, LD, 32 * ks, 16 * n, fr, fq), acc[n]);
;   }
;   bf16_t* st = (bf16_t*)(wsb + WS_RST) + (size_t)((bl * 64 + c) * 4 + hd) * 16384;
; #pragma unroll
;   for (int n = 0; n < 8; ++n) { uint2 w; w.x = pk2(acc[n][0], acc[n][1]); w.y = pk2(acc[n][2], acc[n][3]); *(uint2*)(st + (16 * wid + fr) * 128 + 16 * n + 4 * fq) = w; }
;   __syncthreads();
	v_mfma_f32_16x16x32_bf16 v[12:15], v[40:43], v[36:39], v[12:15]
	ds_read_b64_tr_b16 v[40:41], v6 offset:17472
	ds_read_b64_tr_b16 v[42:43], v6 offset:18560
	s_waitcnt lgkmcnt(0)
	v_mfma_f32_16x16x32_bf16 v[16:19], v[40:43], v[36:39], v[16:19]
	ds_read_b64_tr_b16 v[40:41], v6 offset:17504
	ds_read_b64_tr_b16 v[42:43], v6 offset:18592
	s_waitcnt lgkmcnt(0)
	v_mfma_f32_16x16x32_bf16 v[20:23], v[40:43], v[36:39], v[20:23]
	ds_read_b64_tr_b16 v[40:41], v6 offset:17536
	ds_read_b64_tr_b16 v[42:43], v6 offset:18624
	s_waitcnt lgkmcnt(0)
	v_mfma_f32_16x16x32_bf16 v[24:27], v[40:43], v[36:39], v[24:27]
	ds_read_b64_tr_b16 v[40:41], v6 offset:17568
	ds_read_b64_tr_b16 v[42:43], v6 offset:18656
	s_waitcnt lgkmcnt(0)
	v_mfma_f32_16x16x32_bf16 v[28:31], v[40:43], v[36:39], v[28:31]
	ds_read_b64_tr_b16 v[40:41], v6 offset:17600
	ds_read_b64_tr_b16 v[42:43], v6 offset:18688
	s_waitcnt lgkmcnt(0)
	v_mfma_f32_16x16x32_bf16 v[32:35], v[40:43], v[36:39], v[32:35]
	ds_read_b64_tr_b16 v[40:41], v6 offset:17632
	ds_read_b64_tr_b16 v[42:43], v6 offset:18720
	s_waitcnt lgkmcnt(0)
	v_mfma_f32_16x16x32_bf16 v[0:3], v[40:43], v[36:39], v[0:3]
	ds_read_b64_tr_b16 v[36:37], v7 offset:60928
	ds_read_b64_tr_b16 v[38:39], v7 offset:62016
	ds_read_b64_tr_b16 v[40:41], v6 offset:26112
	ds_read_b64_tr_b16 v[42:43], v6 offset:27200
	s_waitcnt lgkmcnt(0)
	v_mfma_f32_16x16x32_bf16 v[8:11], v[40:43], v[36:39], v[8:11]
	ds_read_b64_tr_b16 v[40:41], v6 offset:26144
	ds_read_b64_tr_b16 v[42:43], v6 offset:27232
	s_waitcnt lgkmcnt(0)
	v_mfma_f32_16x16x32_bf16 v[12:15], v[40:43], v[36:39], v[12:15]
	ds_read_b64_tr_b16 v[40:41], v6 offset:26176
	ds_read_b64_tr_b16 v[42:43], v6 offset:27264
	s_waitcnt lgkmcnt(0)
	v_mfma_f32_16x16x32_bf16 v[16:19], v[40:43], v[36:39], v[16:19]
	ds_read_b64_tr_b16 v[40:41], v6 offset:26208
	ds_read_b64_tr_b16 v[42:43], v6 offset:27296
	s_waitcnt lgkmcnt(0)
	v_mfma_f32_16x16x32_bf16 v[20:23], v[40:43], v[36:39], v[20:23]
	ds_read_b64_tr_b16 v[40:41], v6 offset:26240
	ds_read_b64_tr_b16 v[42:43], v6 offset:27328
	s_waitcnt lgkmcnt(0)
	v_mfma_f32_16x16x32_bf16 v[24:27], v[40:43], v[36:39], v[24:27]
	ds_read_b64_tr_b16 v[40:41], v6 offset:26272
	ds_read_b64_tr_b16 v[42:43], v6 offset:27360
	s_waitcnt lgkmcnt(0)
	v_mfma_f32_16x16x32_bf16 v[28:31], v[40:43], v[36:39], v[28:31]
	ds_read_b64_tr_b16 v[40:41], v6 offset:26304
	ds_read_b64_tr_b16 v[42:43], v6 offset:27392
	s_waitcnt lgkmcnt(0)
	v_mfma_f32_16x16x32_bf16 v[32:35], v[40:43], v[36:39], v[32:35]
	ds_read_b64_tr_b16 v[40:41], v6 offset:26336
	ds_read_b64_tr_b16 v[42:43], v6 offset:27424
	v_cvt_pk_bf16_f32 v6, v8, v9
	v_cvt_pk_bf16_f32 v7, v10, v11
	global_store_dwordx2 v[4:5], v[6:7], off
	v_cvt_pk_bf16_f32 v6, v12, v13
	v_cvt_pk_bf16_f32 v7, v14, v15
	global_store_dwordx2 v[4:5], v[6:7], off offset:32
	v_cvt_pk_bf16_f32 v6, v16, v17
	v_cvt_pk_bf16_f32 v7, v18, v19
	global_store_dwordx2 v[4:5], v[6:7], off offset:64
	v_cvt_pk_bf16_f32 v6, v20, v21
	v_cvt_pk_bf16_f32 v7, v22, v23
	global_store_dwordx2 v[4:5], v[6:7], off offset:96
	v_cvt_pk_bf16_f32 v6, v24, v25
	v_cvt_pk_bf16_f32 v7, v26, v27
	s_waitcnt lgkmcnt(0)
	v_mfma_f32_16x16x32_bf16 v[0:3], v[40:43], v[36:39], v[0:3]
	global_store_dwordx2 v[4:5], v[6:7], off offset:128
	v_cvt_pk_bf16_f32 v6, v28, v29
	v_cvt_pk_bf16_f32 v7, v30, v31
	global_store_dwordx2 v[4:5], v[6:7], off offset:160
	v_cvt_pk_bf16_f32 v6, v32, v33
	v_cvt_pk_bf16_f32 v7, v34, v35
	global_store_dwordx2 v[4:5], v[6:7], off offset:192
	v_cvt_pk_bf16_f32 v0, v0, v1
	v_cvt_pk_bf16_f32 v1, v2, v3
	s_nop 4
	global_store_dwordx2 v[4:5], v[0:1], off offset:224
	s_barrier

; #define otid() otid_(wbase)
; __global__ void __launch_bounds__(NTHR) mega(Params p) {
;     ...
;           else if (u < 448) {
;             scan_unit(p, hf, u - 256, otid());
;             asm volatile("s_waitcnt vmcnt(0)" ::: "memory");
;             __syncthreads();
;             if (otid() == 0) { __builtin_amdgcn_fence(__ATOMIC_RELEASE, "agent"); asm volatile("s_waitcnt vmcnt(0)" ::: "memory"); __hip_atomic_fetch_add(dep, 1, __ATOMIC_RELAXED, __HIP_MEMORY_SCOPE_AGENT); }
.LBB0_351:
	s_or_b64 exec, exec, s[0:1]
	s_barrier
	s_branch .Ldep3_sig
.Ldep3_sig:
	s_waitcnt vmcnt(0)
	s_barrier
	v_mov_b32_e32 v0, v163
	v_cmp_eq_u32_e32 vcc, 0, v0
	s_and_saveexec_b64 s[0:1], vcc
	s_cbranch_execz .Ldep3_sig_j
	buffer_wbl2 sc1
	s_waitcnt vmcnt(0)
	v_mov_b32_e32 v0, 1
	global_atomic_add v161, v0, s[16:17] offset:736
.Ldep3_sig_j:
	s_or_b64 exec, exec, s[0:1]
.LBB0_352:
	s_mov_b64 s[4:5], 0

; #define GSYNC() do { XcdBarrier xb_; xb_.bar = (unsigned*)(ows(p) + WS_BAR); xb_.x = xb_xcc_id(); xb_.st = (volatile LDSP unsigned*)&s_words[0]; xcd_barrier(xb_); } while (0)
; __global__ void __launch_bounds__(NTHR) mega(Params p) {
;     ...
;       GSYNC();
;       {
;         int* my = ctr + phase_id; int* dep = ctr + 64 + phase_id; ++phase_id;
;         bool dep_ok = false;
.LBB0_357:
	s_waitcnt vmcnt(0)
	s_barrier
	s_mov_b64 s[0:1], exec
	v_mov_b32_e32 v0, v163
	v_cmp_eq_u32_e32 vcc, 0, v0
	s_and_b64 s[4:5], s[0:1], vcc
	s_mov_b64 exec, s[4:5]
	s_cbranch_execz .LBB0_409
	buffer_wbl2 sc1
	s_waitcnt vmcnt(0)
	v_mov_b32_e32 v0, 1
	global_atomic_add v161, v0, s[16:17] offset:480
	s_branch .LBB0_409
.LBB0_409:
	s_or_b64 exec, exec, s[0:1]
	v_readlane_b32 s0, v252, 41
	v_readlane_b32 s1, v252, 42
	s_add_u32 s0, s0, s14
	s_addc_u32 s1, s1, s15
	v_writelane_b32 v254, s0, 45
	s_mov_b32 s5, s3
	s_waitcnt lgkmcnt(0)
	v_writelane_b32 v254, s1, 46
	v_readlane_b32 s0, v253, 38
	s_add_u32 s6, s0, s14
	v_readlane_b32 s0, v253, 39
	s_addc_u32 s7, s0, s15
	v_readlane_b32 s0, v254, 25
	s_add_i32 s1, s0, 0x540
	v_writelane_b32 v254, s1, 47
	s_addk_i32 s0, 0x1c0
	v_writelane_b32 v254, s0, 48
	s_lshl_b32 s4, s12, 25
	v_readlane_b32 s0, v252, 48
	v_readlane_b32 s1, v252, 49
	v_writelane_b32 v254, s4, 49
	s_add_u32 s0, s0, s4
	s_addc_u32 s1, s1, 0
	v_writelane_b32 v254, s5, 50
	v_writelane_b32 v254, s0, 51
	s_barrier
	s_nop 0
	v_writelane_b32 v254, s1, 52
	s_mov_b64 s[0:1], 0
	v_writelane_b32 v254, s0, 53
	s_nop 1
	v_writelane_b32 v254, s1, 54
	v_writelane_b32 v254, s6, 55
	s_nop 1
	v_writelane_b32 v254, s7, 56
	s_mov_b32 s0, 0
	s_nop 0
	v_writelane_b32 v255, s0, 44
	v_writelane_b32 v255, s0, 45
	s_branch .LBB0_413

; #define otid() otid_(wbase)
; __global__ void __launch_bounds__(NTHR) mega(Params p) {
;     ...
;           const bool needs = (u >= 448 && u < 576) || (u >= 832);
;           if (needs && !dep_ok) {
;             if (otid() == 0) {
;               unsigned sp = 0;
;               while (__hip_atomic_load(dep, __ATOMIC_RELAXED, __HIP_MEMORY_SCOPE_AGENT) < 192) { __builtin_amdgcn_s_sleep(2); if (++sp > (1u << 22)) break; }
;               __builtin_amdgcn_fence(__ATOMIC_ACQUIRE, "agent");
;               asm volatile("s_waitcnt vmcnt(0)" ::: "memory");
;             }
;             __syncthreads();
;             dep_ok = true;
;           }
.LBB0_431:
	v_writelane_b32 v254, s4, 61
	s_nop 1
	v_writelane_b32 v254, s5, 62
	s_nop 0
	v_readlane_b32 s0, v254, 60
	s_cmpk_lt_u32 s0, 0x100
	s_cbranch_scc1 .Llz_fox
	s_cmpk_lt_u32 s0, 0x1c0
	s_cbranch_scc1 .Llz_scan
	s_cmpk_lt_u32 s0, 0x240
	s_cbranch_scc1 .Llz_done
	s_cmpk_lt_u32 s0, 0x340
	s_cbranch_scc0 .Llz_done
.Llz_fox:
	v_readlane_b32 s0, v255, 44
	s_cmp_lg_u32 s0, 0
	s_cbranch_scc1 .Llz_done
	v_readlane_b32 s4, v254, 45
	v_readlane_b32 s5, v254, 46
	s_add_u32 s4, s4, 0x300
	s_addc_u32 s5, s5, 0
	v_mov_b32_e32 v0, v163
	v_cmp_eq_u32_e32 vcc, 0, v0
	s_and_saveexec_b64 s[0:1], vcc
	s_cbranch_execz .Llz_fox_j
	s_mov_b32 s2, 0x400000
.Llz_fox_spin:
	global_load_dword v0, v161, s[4:5] sc1
	s_waitcnt vmcnt(0)
	v_cmp_lt_i32_e32 vcc, 0x4f, v0
	s_cbranch_vccnz .Llz_fox_got
	s_sleep 2
	s_add_i32 s2, s2, -1
	s_cmp_lg_u32 s2, 0
	s_cbranch_scc1 .Llz_fox_spin

; #define otid() otid_(wbase)
; __global__ void __launch_bounds__(NTHR) mega(Params p) {
;     ...
;           const bool needs = (u >= 448 && u < 576) || (u >= 832);
;           if (needs && !dep_ok) {
;             if (otid() == 0) {
;               unsigned sp = 0;
;               while (__hip_atomic_load(dep, __ATOMIC_RELAXED, __HIP_MEMORY_SCOPE_AGENT) < 192) { __builtin_amdgcn_s_sleep(2); if (++sp > (1u << 22)) break; }
;               __builtin_amdgcn_fence(__ATOMIC_ACQUIRE, "agent");
;               asm volatile("s_waitcnt vmcnt(0)" ::: "memory");
;             }
;             __syncthreads();
;             dep_ok = true;
;           }
.Llz_fox_j:
	s_or_b64 exec, exec, s[0:1]
	s_barrier
	s_mov_b32 s0, 1
	s_nop 0
	v_writelane_b32 v255, s0, 44
	s_branch .Llz_done
.Llz_scan:
	v_readlane_b32 s0, v255, 45
	s_cmp_lg_u32 s0, 0
	s_cbranch_scc1 .Llz_done
	v_readlane_b32 s4, v254, 45
	v_readlane_b32 s5, v254, 46
	s_add_u32 s4, s4, 0x200
	s_addc_u32 s5, s5, 0
	v_mov_b32_e32 v0, v163
	v_cmp_eq_u32_e32 vcc, 0, v0
	s_and_saveexec_b64 s[0:1], vcc
	s_cbranch_execz .Llz_scan_j
	s_mov_b32 s2, 0x400000
.Llz_scan_spin:
	global_load_dword v0, v161, s[4:5] sc1
	s_waitcnt vmcnt(0)
	v_cmp_lt_i32_e32 vcc, 0xff, v0
	s_cbranch_vccnz .Llz_scan_got
	s_sleep 2
	s_add_i32 s2, s2, -1
	s_cmp_lg_u32 s2, 0
	s_cbranch_scc1 .Llz_scan_spin

; DI void unpack8(uint4 v, float* f) { f[0] = bflo(v.x); f[1] = bfhi(v.x); f[2] = bflo(v.y); f[3] = bfhi(v.y); f[4] = bflo(v.z); f[5] = bfhi(v.z); f[6] = bflo(v.w); f[7] = bfhi(v.w); }
; #define otid() otid_(wbase)
; DI void ret_out_unit(const Params& p, int hf, int bl, int c, int hd, unsigned char* shm, int tid, bool dry = false) {
;     ...
;   for (int it = 0; it < 2; ++it) {
;     const int idx = tid + it * NTHR, j = idx >> 3, dg = idx & 7;
;     const bf16_t* base = projb + (size_t)(c * 128 + j) * NP;
;     float q1[8], q2[8], k1[8], k2[8];
;     unpack8(*(const uint4*)(base + C_RQ + hd * 128 + dg * 8), q1); unpack8(*(const uint4*)(base + C_RQ + hd * 128 + 64 + dg * 8), q2);
;     unpack8(*(const uint4*)(base + C_RK + hd * 128 + dg * 8), k1); unpack8(*(const uint4*)(base + C_RK + hd * 128 + 64 + dg * 8), k2);
;     float oq1[8], oq2[8], ok1[8], ok2[8];
; #pragma unroll
;     for (int e = 0; e < 8; ++e) {
;       const float2 t = cs[j * 64 + dg * 8 + e];
; __global__ void __launch_bounds__(NTHR) mega(Params p) {
;     ...
;           }
;           else if (u < 576) { const int k = u - 448; ssd_out_unit(p, layer, hf, k >> 6, k & 63, shm, otid()); }
;           else if (u < 832) { const int k = u - 576 + 256; fox_unit(p, hf, (k >> 3) & 1, k & 7, 31 - (k >> 4), shm, otid()); }
;           else { const int k = u - 832; ret_out_unit(p, hf, k >> 8, (k >> 2) & 63, k & 3, shm, otid()); }
.Llz_scan_j:
	s_or_b64 exec, exec, s[0:1]
	s_barrier
	s_mov_b32 s0, 1
	s_nop 0
	v_writelane_b32 v255, s0, 45
	s_branch .Llz_done
.Llz_done:
	v_readlane_b32 s0, v254, 60
	s_cmpk_gt_i32 s0, 0xff
	s_mov_b64 s[0:1], -1
	s_cbranch_scc0 .LBB0_588
	v_readlane_b32 s0, v254, 60
	s_cmpk_gt_u32 s0, 0x1bf
	s_mov_b64 s[0:1], -1
	s_cbranch_scc0 .LBB0_573
	v_readlane_b32 s0, v254, 60
	s_cmpk_gt_i32 s0, 0x23f
	s_mov_b64 s[0:1], -1
	s_cbranch_scc0 .LBB0_500
	v_readlane_b32 s0, v254, 60
	s_cmpk_gt_u32 s0, 0x33f
	s_mov_b64 s[0:1], -1
	s_cbranch_scc0 .LBB0_468
	v_readlane_b32 s0, v254, 60
	s_add_i32 s5, s0, 0xfffffcc0
	s_lshr_b32 s4, s5, 8
	s_mul_i32 s2, s4, 0x3400000
	s_bfe_u32 s7, s5, 0x60002
	s_and_b32 s6, s23, 3
	s_lshl_b64 s[0:1], s[2:3], 1
	s_add_u32 s8, s38, s0
	v_cvt_f32_ubyte0_e32 v0, s6
	s_addc_u32 s9, s39, s1
	s_lshl_b32 s0, s4, 13
	v_sub_f32_e32 v0, 0xc0a00000, v0
	s_add_i32 s0, s0, s68
	s_lshl_b32 s4, s7, 7
	v_exp_f32_e32 v0, v0
	s_or_b32 s0, s0, s4
	s_lshl_b32 s2, s0, 6
	v_mov_b32_e32 v66, v163
	s_lshl_b64 s[0:1], s[2:3], 3
	v_readlane_b32 s2, v252, 45
	s_add_u32 s0, s2, s0
	v_readlane_b32 s2, v252, 46
	v_sub_f32_e32 v32, 1.0, v0
	v_and_b32_e32 v0, 7, v66
	v_ashrrev_i32_e32 v18, 3, v66
	s_addc_u32 s1, s2, s1
	v_lshlrev_b32_e32 v20, 3, v0
	v_lshlrev_b32_e32 v160, 4, v0
	v_lshlrev_b32_e32 v12, 5, v0
	v_readlane_b32 s2, v254, 0
	v_add_u32_e32 v0, s4, v18
	v_mov_b64_e32 v[16:17], s[8:9]
	v_add_u32_e32 v19, s2, v12
	v_mad_i64_i32 v[0:1], s[8:9], v0, s65, v[16:17]
	s_lshl_b32 s2, s6, 8
	v_lshl_add_u64 v[14:15], v[0:1], 0, s[2:3]
	v_lshl_add_u64 v[4:5], v[14:15], 0, v[160:161]
	v_lshl_add_u64 v[224:225], v[14:15], 0, v[160:161]
	global_load_dwordx4 v[100:103], v[224:225], off
	global_load_dwordx4 v[104:107], v[224:225], off offset:128
	global_load_dwordx4 v[108:111], v[224:225], off offset:1024
	global_load_dwordx4 v[112:115], v[224:225], off offset:1152
	v_lshl_or_b32 v226, v18, 6, v20
	v_mov_b32_e32 v227, v161
	v_lshl_add_u64 v[226:227], v[226:227], 3, s[0:1]
	global_load_dwordx4 v[116:119], v[226:227], off offset:48
	global_load_dwordx4 v[120:123], v[226:227], off offset:32
	global_load_dwordx4 v[124:127], v[226:227], off offset:16
	global_load_dwordx4 v[128:131], v[226:227], off
	v_mov_b32_e32 v228, v12
	v_mov_b32_e32 v229, v161
	v_lshl_add_u64 v[228:229], v[14:15], 0, v[228:229]
	global_load_dwordx4 v[132:135], v[228:229], off offset:2048
	global_load_dwordx4 v[136:139], v[228:229], off offset:2064
	v_add_u32_e32 v230, 64, v18
	v_add_u32_e32 v231, s4, v230
	v_mad_i64_i32 v[232:233], s[8:9], v231, s65, v[16:17]
	v_lshl_add_u64 v[232:233], v[232:233], 0, s[2:3]
	v_lshl_add_u64 v[234:235], v[232:233], 0, v[160:161]
	global_load_dwordx4 v[140:143], v[234:235], off
	global_load_dwordx4 v[144:147], v[234:235], off offset:128
	global_load_dwordx4 v[148:151], v[234:235], off offset:1024
	global_load_dwordx4 v[152:155], v[234:235], off offset:1152
	v_lshl_or_b32 v236, v230, 6, v20
	v_mov_b32_e32 v237, v161
	v_lshl_add_u64 v[236:237], v[236:237], 3, s[0:1]
	global_load_dwordx4 v[156:159], v[236:237], off offset:48
	global_load_dwordx4 v[204:207], v[236:237], off offset:32
	global_load_dwordx4 v[208:211], v[236:237], off offset:16
	global_load_dwordx4 v[212:215], v[236:237], off
	v_mov_b32_e32 v238, v12
	v_mov_b32_e32 v239, v161
	v_lshl_add_u64 v[238:239], v[232:233], 0, v[238:239]
	global_load_dwordx4 v[216:219], v[238:239], off offset:2048
	global_load_dwordx4 v[220:223], v[238:239], off offset:2064
	v_mul_lo_u32 v67, v18, s66
	v_ashrrev_i32_e32 v73, 6, v66
	v_and_b32_e32 v74, 15, v66
	v_lshl_or_b32 v68, v73, 4, v74
	v_bfe_u32 v75, v66, 4, 2
	v_mul_u32_u24_e32 v71, 0x110, v74
	s_waitcnt vmcnt(19)
	v_mov_b32_e32 v0, v100
	v_mov_b32_e32 v1, v101
	v_mov_b32_e32 v2, v102
	v_mov_b32_e32 v3, v103
	v_lshlrev_b32_e32 v26, 16, v0
	v_and_b32_e32 v27, 0xffff0000, v0
	v_lshlrev_b32_e32 v28, 16, v1
	v_and_b32_e32 v29, 0xffff0000, v1
	v_lshlrev_b32_e32 v30, 16, v2
	v_and_b32_e32 v31, 0xffff0000, v2
	v_lshlrev_b32_e32 v21, 16, v3
	v_and_b32_e32 v13, 0xffff0000, v3
	s_waitcnt vmcnt(18)
	v_mov_b32_e32 v0, v104
	v_mov_b32_e32 v1, v105
	v_mov_b32_e32 v2, v106
	v_mov_b32_e32 v3, v107
	v_lshlrev_b32_e32 v33, 16, v0
	v_and_b32_e32 v34, 0xffff0000, v0
	v_lshlrev_b32_e32 v35, 16, v1
	v_and_b32_e32 v36, 0xffff0000, v1
	v_lshlrev_b32_e32 v37, 16, v2
	v_and_b32_e32 v38, 0xffff0000, v2
	v_lshlrev_b32_e32 v39, 16, v3
	v_and_b32_e32 v40, 0xffff0000, v3
	s_waitcnt vmcnt(17)
	v_mov_b32_e32 v0, v108
	v_mov_b32_e32 v1, v109
	v_mov_b32_e32 v2, v110
	v_mov_b32_e32 v3, v111
	v_lshlrev_b32_e32 v41, 16, v0
	v_and_b32_e32 v42, 0xffff0000, v0
	v_lshlrev_b32_e32 v43, 16, v1
	v_and_b32_e32 v44, 0xffff0000, v1
	v_lshlrev_b32_e32 v45, 16, v2
	v_and_b32_e32 v46, 0xffff0000, v2
	v_lshlrev_b32_e32 v47, 16, v3
	v_and_b32_e32 v48, 0xffff0000, v3
	s_waitcnt vmcnt(16)
	v_mov_b32_e32 v0, v112
	v_mov_b32_e32 v1, v113
	v_mov_b32_e32 v2, v114
	v_mov_b32_e32 v3, v115
	v_lshlrev_b32_e32 v49, 16, v0
	v_and_b32_e32 v50, 0xffff0000, v0
	v_lshl_or_b32 v0, v18, 6, v20
	v_lshlrev_b32_e32 v51, 16, v1
	v_and_b32_e32 v52, 0xffff0000, v1
	v_ashrrev_i32_e32 v1, 31, v0
	v_lshl_add_u64 v[22:23], v[0:1], 3, s[0:1]
	v_lshlrev_b32_e32 v53, 16, v2
	v_and_b32_e32 v54, 0xffff0000, v2
	v_lshlrev_b32_e32 v55, 16, v3
	v_and_b32_e32 v56, 0xffff0000, v3
	s_nop 0
	s_waitcnt vmcnt(12)
; DI uint4 pack8(const float* f) { uint4 r; r.x = pk2(f[0], f[1]); r.y = pk2(f[2], f[3]); r.z = pk2(f[4], f[5]); r.w = pk2(f[6], f[7]); return r; }
; DI void ret_out_unit(const Params& p, int hf, int bl, int c, int hd, unsigned char* shm, int tid, bool dry = false) {
;     ...
;     float oq1[8], oq2[8], ok1[8], ok2[8];
; #pragma unroll
;     for (int e = 0; e < 8; ++e) {
;       const float2 t = cs[j * 64 + dg * 8 + e];
;       oq1[e] = q1[e] * t.x - q2[e] * t.y; oq2[e] = q1[e] * t.y + q2[e] * t.x;
;       ok1[e] = (k1[e] * t.x - k2[e] * t.y) * 0.08838834764831845f; ok2[e] = (k1[e] * t.y + k2[e] * t.x) * 0.08838834764831845f;
;     }
;     *(uint4*)(sQ + j * LD + dg * 8) = pack8(oq1); *(uint4*)(sQ + j * LD + 64 + dg * 8) = pack8(oq2);
;     *(uint4*)(sK + j * LD + dg * 8) = pack8(ok1); *(uint4*)(sK + j * LD + 64 + dg * 8) = pack8(ok2);
;     *(uint4*)(sVt + j * LD + dg * 16) = *(const uint4*)(base + C_RV + hd * 128 + dg * 16);
;     *(uint4*)(sVt + j * LD + dg * 16 + 8) = *(const uint4*)(base + C_RV + hd * 128 + dg * 16 + 8);
	v_mov_b32_e32 v0, v116
	v_mov_b32_e32 v1, v117
	v_mov_b32_e32 v2, v118
	v_mov_b32_e32 v3, v119
	v_mov_b32_e32 v4, v120
	v_mov_b32_e32 v5, v121
	v_mov_b32_e32 v6, v122
	v_mov_b32_e32 v7, v123
	v_mov_b32_e32 v8, v124
	v_mov_b32_e32 v9, v125
	v_mov_b32_e32 v10, v126
	v_mov_b32_e32 v11, v127
	v_mov_b32_e32 v22, v128
	v_mov_b32_e32 v23, v129
	v_mov_b32_e32 v24, v130
	v_mov_b32_e32 v25, v131
	v_mul_f32_e32 v57, v23, v33
	v_fma_f32 v57, v22, v26, -v57
	v_mul_f32_e32 v26, v23, v26
	v_fmac_f32_e32 v26, v22, v33
	v_mul_f32_e32 v33, v23, v49
	v_mul_f32_e32 v23, v23, v41
	v_fmac_f32_e32 v23, v22, v49
	v_fma_f32 v33, v22, v41, -v33
	v_mul_f32_e32 v22, 0x3db504f3, v23
	v_mul_f32_e32 v23, v25, v34
	v_fma_f32 v23, v24, v27, -v23
	v_mul_f32_e32 v27, v25, v27
	v_fmac_f32_e32 v27, v24, v34
	v_mul_f32_e32 v34, v25, v50
	v_mul_f32_e32 v25, v25, v42
	v_fmac_f32_e32 v25, v24, v50
	v_fma_f32 v34, v24, v42, -v34
	v_mul_f32_e32 v24, 0x3db504f3, v25
	v_mul_f32_e32 v25, v9, v35
	v_fma_f32 v25, v8, v28, -v25
	v_mul_f32_e32 v28, v9, v28
	v_fmac_f32_e32 v28, v8, v35
	v_mul_f32_e32 v35, v9, v51
	v_mul_f32_e32 v9, v9, v43
	v_fmac_f32_e32 v9, v8, v51
	v_fma_f32 v35, v8, v43, -v35
	v_mul_f32_e32 v8, 0x3db504f3, v9
	v_mul_f32_e32 v9, v11, v36
	v_fma_f32 v9, v10, v29, -v9
	v_mul_f32_e32 v29, v11, v29
	v_fmac_f32_e32 v29, v10, v36
	v_mul_f32_e32 v36, v11, v52
	v_mul_f32_e32 v11, v11, v44
	v_fmac_f32_e32 v11, v10, v52
	v_fma_f32 v36, v10, v44, -v36
	v_mul_f32_e32 v10, 0x3db504f3, v11
	v_mul_f32_e32 v11, v5, v37
	v_fma_f32 v11, v4, v30, -v11
	v_mul_f32_e32 v30, v5, v30
	v_fmac_f32_e32 v30, v4, v37
	v_mul_f32_e32 v37, v5, v53
	v_mul_f32_e32 v5, v5, v45
	v_fmac_f32_e32 v5, v4, v53
	v_fma_f32 v37, v4, v45, -v37
	v_mul_f32_e32 v4, 0x3db504f3, v5
	v_mul_f32_e32 v5, v7, v38
	v_fma_f32 v5, v6, v31, -v5
	v_mul_f32_e32 v31, v7, v31
	v_fmac_f32_e32 v31, v6, v38
	v_mul_f32_e32 v38, v7, v54
	v_mul_f32_e32 v7, v7, v46
	v_fmac_f32_e32 v7, v6, v54
	v_fma_f32 v38, v6, v46, -v38
	v_mul_f32_e32 v6, 0x3db504f3, v7
	v_mul_f32_e32 v7, v1, v39
	v_fma_f32 v7, v0, v21, -v7
	v_mul_f32_e32 v21, v1, v21
	v_fmac_f32_e32 v21, v0, v39
	v_mul_f32_e32 v39, v1, v55
	v_mul_f32_e32 v1, v1, v47
	v_fma_f32 v39, v0, v47, -v39
	v_fmac_f32_e32 v1, v0, v55
	v_mul_f32_e32 v0, v3, v40
	v_fma_f32 v42, v2, v13, -v0
	v_mul_f32_e32 v0, v3, v56
	v_mul_f32_e32 v13, v3, v13
	v_fma_f32 v0, v2, v48, -v0
	v_fmac_f32_e32 v13, v2, v40
	v_mul_f32_e32 v40, 0x3db504f3, v0
	v_mul_f32_e32 v0, v3, v48
	v_fmac_f32_e32 v0, v2, v56
	v_mul_f32_e32 v41, 0x3db504f3, v1
	v_mul_f32_e32 v43, 0x3db504f3, v0
	v_cvt_pk_bf16_f32 v0, v57, v23
	v_cvt_pk_bf16_f32 v1, v25, v9
	v_cvt_pk_bf16_f32 v2, v11, v5
	v_cvt_pk_bf16_f32 v3, v7, v42
	v_add3_u32 v5, 32, v67, v160
	ds_write_b128 v5, v[0:3]
	v_cvt_pk_bf16_f32 v0, v26, v27
	v_cvt_pk_bf16_f32 v1, v28, v29
	v_cvt_pk_bf16_f32 v2, v30, v31
	v_cvt_pk_bf16_f32 v3, v21, v13
	v_mul_f32_e32 v33, 0x3db504f3, v33
	v_mul_f32_e32 v34, 0x3db504f3, v34
	v_mul_f32_e32 v35, 0x3db504f3, v35
	v_mul_f32_e32 v36, 0x3db504f3, v36
	v_mul_f32_e32 v37, 0x3db504f3, v37
	v_mul_f32_e32 v38, 0x3db504f3, v38
	v_mul_f32_e32 v39, 0x3db504f3, v39
	ds_write_b128 v5, v[0:3] offset:128
	v_cvt_pk_bf16_f32 v0, v33, v34
	v_cvt_pk_bf16_f32 v1, v35, v36
	v_cvt_pk_bf16_f32 v2, v37, v38
	v_cvt_pk_bf16_f32 v3, v39, v40
	v_mov_b32_e32 v13, v161
	ds_write_b128 v5, v[0:3] offset:34816
	v_cvt_pk_bf16_f32 v0, v22, v24
	v_cvt_pk_bf16_f32 v1, v8, v10
	v_cvt_pk_bf16_f32 v2, v4, v6
	v_cvt_pk_bf16_f32 v3, v41, v43
	ds_write_b128 v5, v[0:3] offset:34944
	v_lshl_add_u64 v[4:5], v[14:15], 0, v[12:13]
	v_add_u32_e32 v6, v19, v67
	s_waitcnt vmcnt(11)
	v_mov_b32_e32 v0, v132
	v_mov_b32_e32 v1, v133
	v_mov_b32_e32 v2, v134
	v_mov_b32_e32 v3, v135
	ds_write_b128 v6, v[0:3]
	s_waitcnt vmcnt(10)
	v_mov_b32_e32 v0, v136
	v_mov_b32_e32 v1, v137
	v_mov_b32_e32 v2, v138
	v_mov_b32_e32 v3, v139
	ds_write_b128 v6, v[0:3] offset:16
	v_add_u32_e32 v0, 0x200, v66
	v_ashrrev_i32_e32 v14, 3, v0
	v_add_u32_e32 v0, s4, v14
	v_mad_i64_i32 v[0:1], s[8:9], v0, s65, v[16:17]
	v_lshl_add_u64 v[4:5], v[0:1], 0, s[2:3]
	v_lshl_add_u64 v[6:7], v[4:5], 0, v[160:161]
	v_lshl_add_u64 v[4:5], v[4:5], 0, v[12:13]
	s_waitcnt vmcnt(9)
	v_mov_b32_e32 v0, v140
	v_mov_b32_e32 v1, v141
	v_mov_b32_e32 v2, v142
	v_mov_b32_e32 v3, v143
	v_lshlrev_b32_e32 v15, 16, v0
	v_and_b32_e32 v28, 0xffff0000, v0
	v_lshlrev_b32_e32 v29, 16, v1
	v_and_b32_e32 v30, 0xffff0000, v1
	v_lshlrev_b32_e32 v31, 16, v2
	v_and_b32_e32 v33, 0xffff0000, v2
	v_lshlrev_b32_e32 v34, 16, v3
	v_and_b32_e32 v35, 0xffff0000, v3
	s_waitcnt vmcnt(8)
	v_mov_b32_e32 v0, v144
	v_mov_b32_e32 v1, v145
	v_mov_b32_e32 v2, v146
	v_mov_b32_e32 v3, v147
	v_lshlrev_b32_e32 v36, 16, v0
	v_and_b32_e32 v37, 0xffff0000, v0
	v_lshlrev_b32_e32 v38, 16, v1
	v_and_b32_e32 v39, 0xffff0000, v1
	v_lshlrev_b32_e32 v40, 16, v2
	v_and_b32_e32 v41, 0xffff0000, v2
	v_lshlrev_b32_e32 v42, 16, v3
	v_and_b32_e32 v43, 0xffff0000, v3
	s_waitcnt vmcnt(7)
	v_mov_b32_e32 v0, v148
	v_mov_b32_e32 v1, v149
	v_mov_b32_e32 v2, v150
	v_mov_b32_e32 v3, v151
	v_lshlrev_b32_e32 v44, 16, v0
	v_and_b32_e32 v45, 0xffff0000, v0
	v_lshlrev_b32_e32 v46, 16, v1
	v_and_b32_e32 v47, 0xffff0000, v1
	v_lshlrev_b32_e32 v48, 16, v2
	v_and_b32_e32 v49, 0xffff0000, v2
	v_lshlrev_b32_e32 v50, 16, v3
	v_and_b32_e32 v51, 0xffff0000, v3
	s_waitcnt vmcnt(6)
; DI uint4 pack8(const float* f) { uint4 r; r.x = pk2(f[0], f[1]); r.y = pk2(f[2], f[3]); r.z = pk2(f[4], f[5]); r.w = pk2(f[6], f[7]); return r; }
; DI void ret_out_unit(const Params& p, int hf, int bl, int c, int hd, unsigned char* shm, int tid, bool dry = false) {
;     ...
;     float oq1[8], oq2[8], ok1[8], ok2[8];
; #pragma unroll
;     for (int e = 0; e < 8; ++e) {
;       const float2 t = cs[j * 64 + dg * 8 + e];
;       oq1[e] = q1[e] * t.x - q2[e] * t.y; oq2[e] = q1[e] * t.y + q2[e] * t.x;
;       ok1[e] = (k1[e] * t.x - k2[e] * t.y) * 0.08838834764831845f; ok2[e] = (k1[e] * t.y + k2[e] * t.x) * 0.08838834764831845f;
;     }
;     *(uint4*)(sQ + j * LD + dg * 8) = pack8(oq1); *(uint4*)(sQ + j * LD + 64 + dg * 8) = pack8(oq2);
;     *(uint4*)(sK + j * LD + dg * 8) = pack8(ok1); *(uint4*)(sK + j * LD + 64 + dg * 8) = pack8(ok2);
;     *(uint4*)(sVt + j * LD + dg * 16) = *(const uint4*)(base + C_RV + hd * 128 + dg * 16);
;     *(uint4*)(sVt + j * LD + dg * 16 + 8) = *(const uint4*)(base + C_RV + hd * 128 + dg * 16 + 8);
;   }
;   __syncthreads();
;   const int wid = tid >> 6, lane = tid & 63, fr = lane & 15, fq = lane >> 4;
;   const int i_row = 16 * wid + fr;
;   uint4 stv0, stv1, stv2, stv3; uint2 gv8[8];
;   {
;     const bf16_t* st = (const bf16_t*)(wsb + WS_RST) + (size_t)((bl * 64 + c) * 4 + hd) * 16384;
;     { const int e0 = tid >> 3, dg = tid & 7; stv0 = *(const uint4*)(st + e0 * 128 + dg * 16); stv1 = *(const uint4*)(st + e0 * 128 + dg * 16 + 8); stv2 = *(const uint4*)(st + (e0 + 64) * 128 + dg * 16); stv3 = *(const uint4*)(st + (e0 + 64) * 128 + dg * 16 + 8); }
;     const bf16_t* gp0 = projb + (size_t)(c * 128 + i_row) * NP + C_RG + hd * 128 + 4 * fq;
; #pragma unroll
;     for (int n = 0; n < 8; ++n) gv8[n] = *(const uint2*)(gp0 + 16 * n);
;   }
	v_mov_b32_e32 v0, v152
	v_mov_b32_e32 v1, v153
	v_mov_b32_e32 v2, v154
	v_mov_b32_e32 v3, v155
	v_lshlrev_b32_e32 v52, 16, v0
	v_and_b32_e32 v53, 0xffff0000, v0
	v_lshl_or_b32 v0, v14, 6, v20
	v_lshlrev_b32_e32 v54, 16, v1
	v_and_b32_e32 v55, 0xffff0000, v1
	v_ashrrev_i32_e32 v1, 31, v0
	v_lshl_add_u64 v[10:11], v[0:1], 3, s[0:1]
	v_lshlrev_b32_e32 v56, 16, v2
	v_and_b32_e32 v57, 0xffff0000, v2
	v_lshlrev_b32_e32 v58, 16, v3
	v_and_b32_e32 v59, 0xffff0000, v3
	s_and_b32 s0, s5, 0x3ff00
	s_lshl_b32 s1, s7, 2
	s_or_b32 s0, s1, s0
	s_or_b32 s0, s0, s6
	s_lshl_b32 s0, s0, 14
	s_mov_b32 s1, s3
	s_lshl_b64 s[0:1], s[0:1], 1
	v_readlane_b32 s5, v253, 28
	s_add_u32 s0, s5, s0
	v_readlane_b32 s5, v253, 29
	s_addc_u32 s1, s5, s1
	s_waitcnt vmcnt(2)
	v_mov_b32_e32 v0, v156
	v_mov_b32_e32 v1, v157
	v_mov_b32_e32 v2, v158
	v_mov_b32_e32 v3, v159
	v_mov_b32_e32 v6, v204
	v_mov_b32_e32 v7, v205
	v_mov_b32_e32 v8, v206
	v_mov_b32_e32 v9, v207
	v_mov_b32_e32 v20, v208
	v_mov_b32_e32 v21, v209
	v_mov_b32_e32 v22, v210
	v_mov_b32_e32 v23, v211
	v_mov_b32_e32 v24, v212
	v_mov_b32_e32 v25, v213
	v_mov_b32_e32 v26, v214
	v_mov_b32_e32 v27, v215
	v_mul_f32_e32 v10, v25, v36
	v_fma_f32 v10, v24, v15, -v10
	v_mul_f32_e32 v11, v25, v15
	v_mul_f32_e32 v15, v25, v52
	v_mul_f32_e32 v25, v25, v44
	v_fmac_f32_e32 v25, v24, v52
	v_fmac_f32_e32 v11, v24, v36
	v_fma_f32 v15, v24, v44, -v15
	v_mul_f32_e32 v24, 0x3db504f3, v25
	v_mul_f32_e32 v25, v27, v37
	v_fma_f32 v25, v26, v28, -v25
	v_mul_f32_e32 v28, v27, v28
	v_mul_f32_e32 v36, v27, v53
	v_mul_f32_e32 v27, v27, v45
	v_fmac_f32_e32 v27, v26, v53
	v_fmac_f32_e32 v28, v26, v37
	v_fma_f32 v36, v26, v45, -v36
	v_mul_f32_e32 v26, 0x3db504f3, v27
	v_mul_f32_e32 v27, v21, v38
	v_fma_f32 v27, v20, v29, -v27
	v_mul_f32_e32 v29, v21, v29
	v_mul_f32_e32 v37, v21, v54
	v_mul_f32_e32 v21, v21, v46
	v_fmac_f32_e32 v21, v20, v54
	v_fmac_f32_e32 v29, v20, v38
	v_fma_f32 v37, v20, v46, -v37
	v_mul_f32_e32 v20, 0x3db504f3, v21
	v_mul_f32_e32 v21, v23, v39
	v_fma_f32 v21, v22, v30, -v21
	v_mul_f32_e32 v30, v23, v30
	v_mul_f32_e32 v38, v23, v55
	v_mul_f32_e32 v23, v23, v47
	v_fmac_f32_e32 v23, v22, v55
	v_fmac_f32_e32 v30, v22, v39
	v_fma_f32 v38, v22, v47, -v38
	v_mul_f32_e32 v22, 0x3db504f3, v23
	v_mul_f32_e32 v23, v7, v40
	v_fma_f32 v23, v6, v31, -v23
	v_mul_f32_e32 v31, v7, v31
	v_mul_f32_e32 v39, v7, v56
	v_mul_f32_e32 v7, v7, v48
	v_fmac_f32_e32 v7, v6, v56
	v_fmac_f32_e32 v31, v6, v40
	v_fma_f32 v39, v6, v48, -v39
	v_mul_f32_e32 v6, 0x3db504f3, v7
	v_mul_f32_e32 v7, v9, v41
	v_fma_f32 v7, v8, v33, -v7
	v_mul_f32_e32 v33, v9, v33
	v_mul_f32_e32 v40, v9, v57
	v_mul_f32_e32 v9, v9, v49
	v_fmac_f32_e32 v9, v8, v57
	v_fmac_f32_e32 v33, v8, v41
	v_fma_f32 v40, v8, v49, -v40
	v_mul_f32_e32 v8, 0x3db504f3, v9
	v_mul_f32_e32 v9, v1, v42
	v_fma_f32 v9, v0, v34, -v9
	v_mul_f32_e32 v34, v1, v34
	v_mul_f32_e32 v41, v1, v58
	v_mul_f32_e32 v1, v1, v50
	v_fmac_f32_e32 v34, v0, v42
	v_fma_f32 v41, v0, v50, -v41
	v_fmac_f32_e32 v1, v0, v58
	v_mul_f32_e32 v0, v3, v43
	v_fma_f32 v44, v2, v35, -v0
	v_mul_f32_e32 v0, v3, v59
	v_mul_f32_e32 v35, v3, v35
	v_fma_f32 v0, v2, v51, -v0
	v_fmac_f32_e32 v35, v2, v43
	v_mul_f32_e32 v43, 0x3db504f3, v0
	v_mul_f32_e32 v0, v3, v51
	v_fmac_f32_e32 v0, v2, v59
	v_mul_f32_e32 v42, 0x3db504f3, v1
	v_mul_f32_e32 v45, 0x3db504f3, v0
	v_cvt_pk_bf16_f32 v0, v10, v25
	v_cvt_pk_bf16_f32 v1, v27, v21
	v_cvt_pk_bf16_f32 v2, v23, v7
	v_mul_lo_u32 v7, v14, s66
	v_cvt_pk_bf16_f32 v3, v9, v44
	v_add3_u32 v9, 32, v7, v160
	ds_write_b128 v9, v[0:3]
	v_cvt_pk_bf16_f32 v0, v11, v28
	v_cvt_pk_bf16_f32 v1, v29, v30
	v_cvt_pk_bf16_f32 v2, v31, v33
	v_cvt_pk_bf16_f32 v3, v34, v35
	v_mul_f32_e32 v15, 0x3db504f3, v15
	v_mul_f32_e32 v36, 0x3db504f3, v36
	v_mul_f32_e32 v37, 0x3db504f3, v37
	v_mul_f32_e32 v38, 0x3db504f3, v38
	v_mul_f32_e32 v39, 0x3db504f3, v39
	v_mul_f32_e32 v40, 0x3db504f3, v40
	v_mul_f32_e32 v41, 0x3db504f3, v41
	ds_write_b128 v9, v[0:3] offset:128
	v_cvt_pk_bf16_f32 v0, v15, v36
	v_cvt_pk_bf16_f32 v1, v37, v38
	v_cvt_pk_bf16_f32 v2, v39, v40
	v_cvt_pk_bf16_f32 v3, v41, v43
	ds_write_b128 v9, v[0:3] offset:34816
	v_cvt_pk_bf16_f32 v0, v24, v26
	v_cvt_pk_bf16_f32 v1, v20, v22
	v_cvt_pk_bf16_f32 v2, v6, v8
	v_cvt_pk_bf16_f32 v3, v42, v45
	ds_write_b128 v9, v[0:3] offset:34944
	v_add_u32_e32 v6, v19, v7
	v_lshlrev_b32_e32 v8, 7, v18
	v_ashrrev_i32_e32 v9, 31, v8
	v_add_u32_e32 v18, s4, v68
	v_lshlrev_b32_e32 v34, 3, v75
	v_mov_b32_e32 v35, v161
	v_mul_lo_u32 v33, v68, s66
	v_add_u32_e32 v70, 32, v33
	v_lshlrev_b32_e32 v36, 2, v75
	s_waitcnt vmcnt(1)
	v_mov_b32_e32 v0, v216
	v_mov_b32_e32 v1, v217
	v_mov_b32_e32 v2, v218
	v_mov_b32_e32 v3, v219
	ds_write_b128 v6, v[0:3]
	s_waitcnt vmcnt(0)
	v_mov_b32_e32 v0, v220
	v_mov_b32_e32 v1, v221
	v_mov_b32_e32 v2, v222
	v_mov_b32_e32 v3, v223
	ds_write_b128 v6, v[0:3] offset:16
	v_lshl_add_u64 v[0:1], v[8:9], 1, s[0:1]
	v_add_u32_e32 v8, 0x2000, v8
	v_ashrrev_i32_e32 v9, 31, v8
	v_lshl_add_u64 v[8:9], v[8:9], 1, s[0:1]
	v_mad_i64_i32 v[16:17], s[0:1], v18, s65, v[16:17]
	v_lshl_add_u64 v[16:17], v[16:17], 0, s[2:3]
	v_lshlrev_b32_e32 v2, 4, v66
	v_lshl_add_u64 v[16:17], v[16:17], 0, v[34:35]
	s_mov_b64 s[0:1], 0x2400
	v_and_b32_e32 v2, 0x70, v2
	v_lshl_add_u64 v[48:49], v[16:17], 0, s[0:1]
	s_movk_i32 s0, 0x2000
	v_lshlrev_b32_e32 v160, 1, v2
	v_add_co_u32_e32 v16, vcc, s0, v16
	v_lshl_add_u64 v[4:5], v[0:1], 0, v[160:161]
	v_lshl_add_u64 v[12:13], v[8:9], 0, v[160:161]
	v_addc_co_u32_e32 v17, vcc, 0, v17, vcc
	s_waitcnt lgkmcnt(0)
	s_barrier
; DI unsigned pk2(float lo, float hi) { unsigned r; asm volatile("v_cvt_pk_bf16_f32 %0, %1, %2" : "=v"(r) : "v"(lo), "v"(hi)); return r; }
; DI f32x4 mmaT(bf16x8 a_m, bf16x8 b_n, f32x4 c) { return __builtin_amdgcn_mfma_f32_16x16x32_bf16(b_n, a_m, c, 0, 0, 0); }
; DI void ret_out_unit(const Params& p, int hf, int bl, int c, int hd, unsigned char* shm, int tid, bool dry = false) {
;     ...
;   uint4 stv0, stv1, stv2, stv3; uint2 gv8[8];
;   {
;     const bf16_t* st = (const bf16_t*)(wsb + WS_RST) + (size_t)((bl * 64 + c) * 4 + hd) * 16384;
;     { const int e0 = tid >> 3, dg = tid & 7; stv0 = *(const uint4*)(st + e0 * 128 + dg * 16); stv1 = *(const uint4*)(st + e0 * 128 + dg * 16 + 8); stv2 = *(const uint4*)(st + (e0 + 64) * 128 + dg * 16); stv3 = *(const uint4*)(st + (e0 + 64) * 128 + dg * 16 + 8); }
;     const bf16_t* gp0 = projb + (size_t)(c * 128 + i_row) * NP + C_RG + hd * 128 + 4 * fq;
; #pragma unroll
;     for (int n = 0; n < 8; ++n) gv8[n] = *(const uint2*)(gp0 + 16 * n);
;   }
;   {
;     bf16x8 aq[4];
; #pragma unroll
;     for (int ks = 0; ks < 4; ++ks) aq[ks] = ldf(sQ, LD, 16 * wid, 32 * ks, fr, fq);
; #pragma unroll
;     for (int n = 0; n < 8; ++n) {
;       if (n <= (wid | 1)) {
;         uint2 w; w.x = 0u; w.y = 0u;
;         if (n <= wid) {
;           f32x4 s = (f32x4){0.f, 0.f, 0.f, 0.f};
; #pragma unroll
;           for (int ks = 0; ks < 4; ++ks) s = mmaT(aq[ks], ldf(sK, LD, 16 * n, 32 * ks, fr, fq), s);
;           float r[4];
; #pragma unroll
;           for (int j = 0; j < 4; ++j) { const int d = i_row - (16 * n + 4 * fq + j); r[j] = (d >= 0) ? s[j] * __expf(lg * (float)d) : 0.f; }
;           w.x = pk2(r[0], r[1]); w.y = pk2(r[2], r[3]);
;         }
;         *(uint2*)(sS + i_row * LD + 16 * n + 4 * fq) = w;
;       }
;     }
	global_load_dwordx4 v[0:3], v[4:5], off offset:16
	s_nop 0
	global_load_dwordx4 v[4:7], v[4:5], off
	s_nop 0
	global_load_dwordx4 v[8:11], v[12:13], off offset:16
	s_nop 0
	global_load_dwordx4 v[12:15], v[12:13], off
	s_nop 0
	global_load_dwordx2 v[64:65], v[16:17], off offset:1024
	global_load_dwordx2 v[62:63], v[48:49], off offset:32
	global_load_dwordx2 v[60:61], v[48:49], off offset:64
	global_load_dwordx2 v[58:59], v[48:49], off offset:96
	global_load_dwordx2 v[56:57], v[48:49], off offset:128
	global_load_dwordx2 v[54:55], v[48:49], off offset:160
	global_load_dwordx2 v[52:53], v[48:49], off offset:192
	global_load_dwordx2 v[50:51], v[48:49], off offset:224
	s_mov_b32 s0, 0x800000
	v_cmp_gt_f32_e32 vcc, s0, v32
	s_and_b64 s[0:1], vcc, exec
	s_cselect_b32 s0, 32, 0
	v_ldexp_f32 v32, v32, s0
	v_log_f32_e32 v32, v32
	v_and_b32_e32 v35, 48, v66
	v_add_u32_e32 v16, v70, v35
	ds_read_b128 v[28:31], v16
	ds_read_b128 v[24:27], v16 offset:64
	ds_read_b128 v[20:23], v16 offset:128
	ds_read_b128 v[16:19], v16 offset:192
	v_mul_f32_e32 v37, 0x3f317217, v32
	s_mov_b32 s0, 0x3f317217
	v_fma_f32 v37, v32, s0, -v37
	v_fmac_f32_e32 v37, 0x3377d1cf, v32
	s_mov_b32 s0, 0x7f800000
	v_fmac_f32_e32 v37, 0x3f317217, v32
	v_cmp_lt_f32_e64 s[0:1], |v32|, s0
	v_add_u32_e32 v38, 32, v35
	s_nop 0
	v_cndmask_b32_e64 v32, v32, v37, s[0:1]
	v_cndmask_b32_e32 v37, 0, v201, vcc
	v_readlane_b32 s0, v254, 1
	v_sub_f32_e32 v69, v32, v37
	v_cmp_lt_i32_e32 vcc, -1, v73
	v_add3_u32 v37, s0, v33, v34
	s_and_saveexec_b64 s[0:1], vcc
	s_cbranch_execz .LBB0_439
	v_mad_u32_u24 v39, v74, s66, v38
	ds_read_b128 v[32:35], v39 offset:34816
	ds_read_b128 v[40:43], v39 offset:34880
	s_waitcnt lgkmcnt(1)
	v_mfma_f32_16x16x32_bf16 v[32:35], v[32:35], v[28:31], 0
	s_waitcnt lgkmcnt(0)
	v_mfma_f32_16x16x32_bf16 v[32:35], v[40:43], v[24:27], v[32:35]
	ds_read_b128 v[40:43], v39 offset:34944
	s_waitcnt lgkmcnt(0)
	v_mfma_f32_16x16x32_bf16 v[32:35], v[40:43], v[20:23], v[32:35]
	ds_read_b128 v[40:43], v39 offset:35008
	v_sub_u32_e32 v39, v68, v36
	v_cmp_lt_i32_e32 vcc, -1, v39
	v_cvt_f32_u32_e32 v39, v39
	s_waitcnt lgkmcnt(0)
	v_mfma_f32_16x16x32_bf16 v[32:35], v[40:43], v[16:19], v[32:35]
	v_mul_f32_e32 v39, v69, v39
	v_mul_f32_e32 v39, 0x3fb8aa3b, v39
	v_exp_f32_e32 v39, v39
	s_nop 4
	v_mul_f32_e32 v32, v39, v32
	v_xad_u32 v39, v36, -1, v68
	v_cndmask_b32_e32 v32, 0, v32, vcc
	v_cmp_lt_i32_e32 vcc, -1, v39
	v_cvt_f32_u32_e32 v39, v39
	v_mul_f32_e32 v39, v69, v39
	v_mul_f32_e32 v39, 0x3fb8aa3b, v39
	v_exp_f32_e32 v39, v39
	s_nop 0
	v_mul_f32_e32 v33, v39, v33
	v_or_b32_e32 v39, 2, v36
	v_sub_u32_e32 v39, v68, v39
	v_cndmask_b32_e32 v33, 0, v33, vcc
	v_cmp_lt_i32_e32 vcc, -1, v39
	v_cvt_f32_u32_e32 v39, v39
	v_cvt_pk_bf16_f32 v32, v32, v33
	v_mul_f32_e32 v39, v69, v39
	v_mul_f32_e32 v39, 0x3fb8aa3b, v39
	v_exp_f32_e32 v39, v39
	s_nop 0
	v_mul_f32_e32 v34, v39, v34
	v_or_b32_e32 v39, 3, v36
	v_sub_u32_e32 v39, v68, v39
	v_cndmask_b32_e32 v34, 0, v34, vcc
	v_cmp_lt_i32_e32 vcc, -1, v39
	v_cvt_f32_u32_e32 v39, v39
	v_mul_f32_e32 v39, v69, v39
	v_mul_f32_e32 v39, 0x3fb8aa3b, v39
	v_exp_f32_e32 v39, v39
	s_nop 0
	v_mul_f32_e32 v35, v39, v35
	v_cndmask_b32_e32 v35, 0, v35, vcc
	v_cvt_pk_bf16_f32 v33, v34, v35
	ds_write_b64 v37, v[32:33]
	v_cmp_lt_u32_e32 vcc, 63, v66
	v_mov_b32_e32 v32, 0
	v_mov_b32_e32 v33, 0
	s_and_saveexec_b64 s[4:5], vcc
	s_cbranch_execz .LBB0_438
	v_add_u32_e32 v39, v38, v71
	ds_read_b128 v[32:35], v39 offset:39168
	ds_read_b128 v[40:43], v39 offset:39232
	s_waitcnt lgkmcnt(1)
	v_mfma_f32_16x16x32_bf16 v[32:35], v[32:35], v[28:31], 0
	s_waitcnt lgkmcnt(0)
	v_mfma_f32_16x16x32_bf16 v[32:35], v[40:43], v[24:27], v[32:35]
	ds_read_b128 v[40:43], v39 offset:39296
	s_waitcnt lgkmcnt(0)
	v_mfma_f32_16x16x32_bf16 v[32:35], v[40:43], v[20:23], v[32:35]
	ds_read_b128 v[40:43], v39 offset:39360
	v_or_b32_e32 v39, 16, v36
	v_sub_u32_e32 v39, v68, v39
	v_cmp_lt_i32_e32 vcc, -1, v39
	v_cvt_f32_u32_e32 v39, v39
	s_waitcnt lgkmcnt(0)
	v_mfma_f32_16x16x32_bf16 v[32:35], v[40:43], v[16:19], v[32:35]
	v_mul_f32_e32 v39, v69, v39
	v_mul_f32_e32 v39, 0x3fb8aa3b, v39
	v_exp_f32_e32 v39, v39
	s_nop 4
	v_mul_f32_e32 v32, v39, v32
	v_or_b32_e32 v39, 17, v36
	v_sub_u32_e32 v39, v68, v39
	v_cndmask_b32_e32 v32, 0, v32, vcc
	v_cmp_lt_i32_e32 vcc, -1, v39
	v_cvt_f32_u32_e32 v39, v39
	v_mul_f32_e32 v39, v69, v39
	v_mul_f32_e32 v39, 0x3fb8aa3b, v39
	v_exp_f32_e32 v39, v39
	s_nop 0
	v_mul_f32_e32 v33, v39, v33
	v_or_b32_e32 v39, 18, v36
	v_sub_u32_e32 v39, v68, v39
	v_cndmask_b32_e32 v33, 0, v33, vcc
	v_cmp_lt_i32_e32 vcc, -1, v39
	v_cvt_f32_u32_e32 v39, v39
	v_cvt_pk_bf16_f32 v32, v32, v33
	v_mul_f32_e32 v39, v69, v39
	v_mul_f32_e32 v39, 0x3fb8aa3b, v39
	v_exp_f32_e32 v39, v39
	s_nop 0
	v_mul_f32_e32 v34, v39, v34
	v_or_b32_e32 v39, 19, v36
	v_sub_u32_e32 v39, v68, v39
	v_cndmask_b32_e32 v34, 0, v34, vcc
	v_cmp_lt_i32_e32 vcc, -1, v39
	v_cvt_f32_u32_e32 v39, v39
	v_mul_f32_e32 v39, v69, v39
	v_mul_f32_e32 v39, 0x3fb8aa3b, v39
	v_exp_f32_e32 v39, v39
	s_nop 0
	v_mul_f32_e32 v35, v39, v35
	v_cndmask_b32_e32 v35, 0, v35, vcc
	v_cvt_pk_bf16_f32 v33, v34, v35
